# ada items dealt over all 256 workgroups (3 per CU instead of 8 on 96 CUs: float-atomic issue rate per CU was the limit); transpose deal rebalanced
# speedup vs baseline: 1.0458x; 1.0104x over previous
; __global__ void __launch_bounds__(512, 2) mega_fwd(Args a) {
;     ...
;         for (int it = gw; it < 768; it += NGW) {
;             const int cb = it % 24, kc = it / 24, n0 = cb * 256 + lane * 4, k0 = kc * 32;
;             f32x4 acc[8];
; #pragma unroll
;             for (int b = 0; b < 8; ++b) acc[b] = (f32x4){0.f, 0.f, 0.f, 0.f};
; #pragma unroll 8
;             for (int kk = 0; kk < 32; ++kk) {
;                 const f32x4 w = *(const f32x4*)(KA->w_ada + (size_t)(k0 + kk) * 6144 + n0);
; #pragma unroll
;                 for (int b = 0; b < 8; ++b) acc[b] += cact[b * DM + k0 + kk] * w;
;             }
;             if (kc == 0) { const f32x4 bv = *(const f32x4*)(KA->b_ada + n0);
; #pragma unroll
;                 for (int b = 0; b < 8; ++b) acc[b] += bv; }
; #pragma unroll
;             for (int b = 0; b < 8; ++b)
; #pragma unroll
;                 for (int e = 0; e < 4; ++e) __hip_atomic_fetch_add(ADA + b * 6144 + n0 + e, acc[b][e], __ATOMIC_RELAXED, __HIP_MEMORY_SCOPE_AGENT);
;         }
.LBB0_10:
	v_readfirstlane_b32 s8, v195
	s_lshr_b32 s8, s8, 6
	s_mul_i32 s8, s8, s28
	s_add_i32 s3, s8, s3
	s_cmpk_lt_i32 s3, 0x300
	s_cbranch_scc1 .LBB0_12
	s_lshl_b32 s18, s28, 3
	s_cbranch_execz .LBB0_13
	s_branch .LBB0_19

; __global__ void __launch_bounds__(512, 2) mega_fwd(Args a) {
;     ...
;         for (int it = (gw + NGW - (768 % NGW)) % NGW; it < NITEMS; it += NGW) {
;             int r = it;
;             if (r < I_IN) { const int kb = r / 45, n0 = 32 * (r % 45); tr_item(KA->w_in, DM, 1440, WIN, 64 * kb, n0, n0 + (n0 >= 416 ? 96 : 0), scr, lane); continue; } r -= I_IN;
.LBB0_19:
	s_abs_i32 s9, s18
	v_cvt_f32_u32_e32 v1, s9
	s_ashr_i32 s3, s2, 31
	s_lshr_b32 s10, s3, 29
	s_add_i32 s10, s2, s10
	v_rcp_iflag_f32_e32 v1, v1
	s_ashr_i32 s11, s10, 3
	s_and_b32 s10, s10, -8
	s_sub_i32 s24, s2, s10
	v_mul_f32_e32 v1, 0x4f7ffffe, v1
	v_cvt_u32_f32_e32 v1, v1
	s_lshr_b32 s10, s28, 3
	s_mul_i32 s10, s10, s24
	v_writelane_b32 v255, s11, 5
	s_add_i32 s12, s10, s11
	s_sub_i32 s10, 0, s9
	v_readfirstlane_b32 s11, v1
	s_mul_i32 s10, s10, s11
	s_mul_hi_u32 s10, s11, s10
	s_add_i32 s13, s11, s10
	s_mul_hi_u32 s10, s13, 0x300
	s_mul_i32 s10, s10, s9
	s_sub_i32 s10, 0x300, s10
	s_sub_i32 s11, s10, s9
	s_cmp_ge_u32 s10, s9
	s_cselect_b32 s10, s11, s10
	s_sub_i32 s11, s10, s9
	s_cmp_ge_u32 s10, s9
	s_cselect_b32 s16, s11, s10
	s_and_b64 s[10:11], exec, s[14:15]
	s_cselect_b32 s54, s12, s2
	v_readfirstlane_b32 s8, v195
	s_add_i32 s11, s54, s28
	s_lshr_b32 s10, s8, 6
	s_lshl_b32 s11, s11, 3
	s_add_i32 s11, s11, s10
	s_sub_i32 s10, s11, s16
	s_ashr_i32 s11, s10, 31
	s_abs_i32 s10, s10
	s_mul_hi_u32 s12, s10, s13
	s_mul_i32 s12, s12, s9
	s_sub_i32 s10, s10, s12
	s_sub_i32 s12, s10, s9
	s_cmp_ge_u32 s10, s9
	s_cselect_b32 s10, s12, s10
	s_sub_i32 s12, s10, s9
	s_cmp_ge_u32 s10, s9
	s_cselect_b32 s9, s12, s10
	s_xor_b32 s9, s9, s11
	s_sub_i32 s19, s9, s11
	s_lshr_b32 s10, s8, 6
	s_add_i32 s10, s10, 5
	s_and_b32 s10, s10, 7
	s_mul_i32 s10, s10, s28
	s_add_i32 s19, s10, s54
	s_cmpk_gt_i32 s19, 0x15ef
	s_barrier
	s_cbranch_scc1 .LBB0_42
	s_lshl_b32 s8, s8, 8
	s_and_b32 s8, s8, 0x7fffc000
	s_add_i32 s33, s8, 0
	s_lshl_b32 s8, s19, 1
	s_add_i32 s36, s8, 0xffffdf20
	s_lshl_b32 s8, s19, 4
	s_lshl_b32 s34, s19, 5
	s_lshl_b32 s35, s18, 5
	s_lshl_b32 s37, s18, 1
	s_add_i32 s38, s8, 0xffffcd00
	s_lshl_b32 s39, s18, 4
	v_mov_b32_e32 v3, 0
	s_mov_b64 s[8:9], 0x1300000
	s_mov_b64 s[10:11], 0x800000
	s_mov_b64 s[12:13], 0x600000
	s_mov_b32 s40, 0x580000
	s_mov_b64 s[16:17], 0x500000
	s_movk_i32 s41, 0x1680
	s_mov_b64 s[20:21], 0x200000
	s_branch .LBB0_22
